# GU and OUT GEMM: first K-iteration peeled with C=0 first-touch MFMAs; 128 accumulator-zeroing v_mov per tile removed
# baseline (speedup 1.0000x reference)
;     __host__ __device__ bool next(int i, Unit& u) const { if (!base.next(i >> 1, u)) return false; if (i & 1) { u.pm += 64; u.pn += 8; } return true; }
; #define PG8_STAGE(bufoff, gbase, voff) do { _Pragma("unroll") for (int _i = 0; _i < 2; ++_i) \
;         __builtin_amdgcn_global_load_lds((const unsigned*)((const char*)(gbase) + (voff)[_i]), (PG8_LAS unsigned*)(lds + (bufoff) + ldsw + _i * 8192), 16, 0, 0); } while (0)
; #define PG8_LDA(dst, b, h) do { _Pragma("unroll") for (int m = 0; m < 4; ++m) _Pragma("unroll") for (int k = 0; k < 2; ++k) dst[m][k] = *(const PG8_LAS bf16x8*)(lds + PG8_SA(b, h) + aoff + m * 2048 + k * 1024); } while (0)
; #define PG8_WAIT_V(n) asm volatile("s_waitcnt vmcnt(" #n ")" ::: "memory")
; #define PG8_WAIT_L(n) asm volatile("s_waitcnt lgkmcnt(" #n ")" ::: "memory")
; #define PG8_BAR __builtin_amdgcn_s_barrier()
; template <class Epi, class Sched, bool ALIGN_EPI = false, bool SP2 = false>
; __device__ __forceinline__ void gemm_phase(PG8_LAS unsigned char* lds, const Gemm g, const Sched& S, const Epi& E) {
;     ...
;         const bool has_next = S.next(ui + 1, nxt);
;         const char* nA = has_next ? (const char*)g.A + (size_t)nxt.pm * tstep : cA; const char* nB = has_next ? (const char*)g.Bt + (size_t)nxt.pn * tstep : cB;
;         for (int t = 0; t < nt; t += 2) {
;             const bool last = (t == nt - 2);
;             const char* a1 = cA + (size_t)(t + 1) * kstep;
;             const char* a2 = last ? nA : cA + (size_t)(t + 2) * kstep; const char* b2 = last ? nB : cB + (size_t)(t + 2) * kstep;
;             const char* a3 = a2 + kstep; const char* b3 = b2 + kstep;
;             if (last && has_next) S.a_ready(nxt);
;             if constexpr (SP2) {
;             PG8_LDB(B0, 0, 0); PG8_LDB(B1, 0, 1); PG8_SCHED; PG8_LDA(At, 0, 0); PG8_STAGE(PG8_SA(1, 1), a1 + hstep, voffA);
;             PG8_WAIT_V(8); PG8_WAIT_L(0); PG8_BAR; PG8_MMA(0, 0, At, B0); PG8_MMA(0, 1, At, B1); PG8_BAR; PG8_SCHED;
;             PG8_LDA(At, 0, 1); PG8_STAGE(PG8_SB(0, 0), b2, voffB); PG8_STAGE(PG8_SB(0, 1), b2 + hstep, voffB); PG8_STAGE(PG8_SA(0, 0), a2, voffA);
;     ...
;         for (int a = 0; a < 2; ++a)
; #pragma unroll
;             for (int b = 0; b < 2; ++b)
; #pragma unroll
;                 for (int m = 0; m < 4; ++m)
; #pragma unroll
;                     for (int n = 0; n < 2; ++n) acc[a][b][m][n] = (f32x4){0.f, 0.f, 0.f, 0.f};
.LBB0_24:
	s_ashr_i32 s55, s54, 31
	s_lshl_b64 s[76:77], s[54:55], 20
	s_add_u32 s76, s8, s76
	s_addc_u32 s77, s9, s77
	s_and_b64 s[78:79], s[74:75], exec
	s_cselect_b32 s55, s77, s53
	s_cselect_b32 s83, s76, s52
	s_ashr_i32 s73, s72, 31
	s_lshl_b64 s[78:79], s[72:73], 20
	s_add_u32 s78, s0, s78
	s_addc_u32 s79, s1, s79
	s_and_b64 s[80:81], s[74:75], exec
	s_cselect_b32 s73, s79, s5
	s_cselect_b32 s84, s78, s4
	s_add_u32 s80, s52, 0x80080
	s_addc_u32 s81, s53, 0
	s_add_u32 s85, s4, 0x100
	s_addc_u32 s86, s5, 0
	s_mov_b32 s87, -2
	v_add_u32_e32 v200, 0x10000, v139
	s_add_i32 s88, 0, 0x10000
	s_add_i32 s90, 0, 0x14000
	ds_read_b128 v[142:145], v200
	ds_read_b128 v[146:149], v200 offset:1024
	ds_read_b128 v[150:153], v200 offset:2048
	ds_read_b128 v[154:157], v200 offset:3072
	ds_read_b128 v[164:167], v200 offset:16384
	ds_read_b128 v[168:171], v200 offset:17408
	ds_read_b128 v[172:175], v200 offset:18432
	ds_read_b128 v[176:179], v200 offset:19456
	s_add_i32 m0, s29, 0xc000
	ds_read_b128 v[180:183], v141
	ds_read_b128 v[184:187], v141 offset:1024
	ds_read_b128 v[188:191], v141 offset:2048
	ds_read_b128 v[192:195], v141 offset:3072
	ds_read_b128 v[196:199], v141 offset:4096
	ds_read_b128 v[222:225], v141 offset:5120
	ds_read_b128 v[226:229], v141 offset:6144
	ds_read_b128 v[230:233], v141 offset:7168
	global_load_lds_dwordx4 v134, s[80:81]
	s_add_i32 m0, s29, 0xe000
	s_nop 0
	global_load_lds_dwordx4 v136, s[80:81]
	s_add_u32 s4, s80, 0xfff80080
	s_addc_u32 s5, s81, -1
	s_cmp_eq_u32 s87, 28
	s_cselect_b32 s53, s55, s5
	s_cselect_b32 s52, s83, s4
	s_cselect_b32 s5, s73, s86
	s_cselect_b32 s4, s84, s85
	s_waitcnt vmcnt(8)
	s_waitcnt lgkmcnt(0)
	s_barrier
	s_waitcnt lgkmcnt(0)
	v_mfma_f32_16x16x32_bf16 v[124:127], v[142:145], v[180:183], 0
	v_mfma_f32_16x16x32_bf16 v[120:123], v[150:153], v[180:183], 0
	v_mfma_f32_16x16x32_bf16 v[116:119], v[142:145], v[188:191], 0
	v_mfma_f32_16x16x32_bf16 v[112:115], v[150:153], v[188:191], 0
	v_mfma_f32_16x16x32_bf16 v[100:103], v[142:145], v[196:199], 0
	v_mfma_f32_16x16x32_bf16 v[96:99], v[150:153], v[196:199], 0
	v_mfma_f32_16x16x32_bf16 v[84:87], v[142:145], v[226:229], 0
	v_mfma_f32_16x16x32_bf16 v[80:83], v[150:153], v[226:229], 0
	v_mfma_f32_16x16x32_bf16 v[124:127], v[146:149], v[184:187], v[124:127]
	v_mfma_f32_16x16x32_bf16 v[120:123], v[154:157], v[184:187], v[120:123]
	v_mfma_f32_16x16x32_bf16 v[116:119], v[146:149], v[192:195], v[116:119]
	v_mfma_f32_16x16x32_bf16 v[112:115], v[154:157], v[192:195], v[112:115]
	v_mfma_f32_16x16x32_bf16 v[100:103], v[146:149], v[222:225], v[100:103]
	v_mfma_f32_16x16x32_bf16 v[96:99], v[154:157], v[222:225], v[96:99]
	v_mfma_f32_16x16x32_bf16 v[84:87], v[146:149], v[230:233], v[84:87]
	v_mfma_f32_16x16x32_bf16 v[80:83], v[154:157], v[230:233], v[80:83]
	v_mfma_f32_16x16x32_bf16 v[108:111], v[164:167], v[180:183], 0
	v_mfma_f32_16x16x32_bf16 v[104:107], v[172:175], v[180:183], 0
	v_mfma_f32_16x16x32_bf16 v[92:95], v[164:167], v[188:191], 0
	v_mfma_f32_16x16x32_bf16 v[88:91], v[172:175], v[188:191], 0
	v_mfma_f32_16x16x32_bf16 v[76:79], v[164:167], v[196:199], 0
	v_mfma_f32_16x16x32_bf16 v[72:75], v[172:175], v[196:199], 0
	v_mfma_f32_16x16x32_bf16 v[68:71], v[164:167], v[226:229], 0
	v_mfma_f32_16x16x32_bf16 v[64:67], v[172:175], v[226:229], 0
	v_mfma_f32_16x16x32_bf16 v[108:111], v[168:171], v[184:187], v[108:111]
	v_mfma_f32_16x16x32_bf16 v[104:107], v[176:179], v[184:187], v[104:107]
	v_mfma_f32_16x16x32_bf16 v[92:95], v[168:171], v[192:195], v[92:95]
	v_mfma_f32_16x16x32_bf16 v[88:91], v[176:179], v[192:195], v[88:91]
	v_mfma_f32_16x16x32_bf16 v[76:79], v[168:171], v[222:225], v[76:79]
	v_mfma_f32_16x16x32_bf16 v[72:75], v[176:179], v[222:225], v[72:75]
	v_mfma_f32_16x16x32_bf16 v[68:71], v[168:171], v[230:233], v[68:71]
	v_mfma_f32_16x16x32_bf16 v[64:67], v[176:179], v[230:233], v[64:67]
	s_barrier
	s_add_i32 s88, s88, s28
	s_mov_b32 m0, s88
	ds_read_b128 v[180:183], v141 offset:16384
	ds_read_b128 v[184:187], v141 offset:17408
	ds_read_b128 v[188:191], v141 offset:18432
	ds_read_b128 v[192:195], v141 offset:19456
	ds_read_b128 v[196:199], v141 offset:20480
	ds_read_b128 v[222:225], v141 offset:21504
	ds_read_b128 v[226:229], v141 offset:22528
	ds_read_b128 v[230:233], v141 offset:23552
	global_load_lds_dwordx4 v160, s[4:5]
	s_add_i32 m0, s88, 0x2000
	s_add_u32 s88, s4, 0x80000
	s_addc_u32 s89, s5, 0
	s_add_i32 s90, s90, s28
	global_load_lds_dwordx4 v128, s[4:5]
	s_mov_b32 m0, s90
	s_nop 0
	global_load_lds_dwordx4 v160, s[88:89]
	s_add_i32 m0, s90, 0x2000
	s_nop 0
	global_load_lds_dwordx4 v128, s[88:89]
	s_mov_b32 m0, s29
	s_nop 0
	global_load_lds_dwordx4 v132, s[52:53]
	s_mov_b32 m0, s45
	s_nop 0
	global_load_lds_dwordx4 v130, s[52:53]
	s_add_u32 s98, s52, 0x80
	s_addc_u32 s99, s53, 0
	s_waitcnt vmcnt(8)
	s_waitcnt lgkmcnt(0)
	s_barrier
; #define PG8_STAGE(bufoff, gbase, voff) do { _Pragma("unroll") for (int _i = 0; _i < 2; ++_i) \
;         __builtin_amdgcn_global_load_lds((const unsigned*)((const char*)(gbase) + (voff)[_i]), (PG8_LAS unsigned*)(lds + (bufoff) + ldsw + _i * 8192), 16, 0, 0); } while (0)
; #define PG8_LDA(dst, b, h) do { _Pragma("unroll") for (int m = 0; m < 4; ++m) _Pragma("unroll") for (int k = 0; k < 2; ++k) dst[m][k] = *(const PG8_LAS bf16x8*)(lds + PG8_SA(b, h) + aoff + m * 2048 + k * 1024); } while (0)
; #define PG8_LDB(dst, b, h) do { _Pragma("unroll") for (int n = 0; n < 2; ++n) _Pragma("unroll") for (int k = 0; k < 2; ++k) dst[n][k] = *(const PG8_LAS bf16x8*)(lds + PG8_SB(b, h) + boff + n * 2048 + k * 1024); } while (0)
; #define PG8_MMA(ai, bj, At, Bt) do { __builtin_amdgcn_s_setprio(1); _Pragma("unroll") for (int m = 0; m < 4; ++m) _Pragma("unroll") for (int n = 0; n < 2; ++n) _Pragma("unroll") for (int k = 0; k < 2; ++k) \
;         acc[ai][bj][m][n] = __builtin_amdgcn_mfma_f32_16x16x32_bf16(Bt[n][k], At[m][k], acc[ai][bj][m][n], 0, 0, 0); __builtin_amdgcn_s_setprio(0); } while (0)
; #define PG8_WAIT_V(n) asm volatile("s_waitcnt vmcnt(" #n ")" ::: "memory")
; #define PG8_WAIT_L(n) asm volatile("s_waitcnt lgkmcnt(" #n ")" ::: "memory")
; #define PG8_BAR __builtin_amdgcn_s_barrier()
; #define PG8_SCHED __builtin_amdgcn_sched_barrier(0)
; template <class Epi, class Sched, bool ALIGN_EPI = false, bool SP2 = false>
; __device__ __forceinline__ void gemm_phase(PG8_LAS unsigned char* lds, const Gemm g, const Sched& S, const Epi& E) {
;     ...
;             PG8_WAIT_V(8); PG8_WAIT_L(0); PG8_BAR; PG8_MMA(0, 0, At, B0); PG8_MMA(0, 1, At, B1); PG8_BAR; PG8_SCHED;
;             PG8_LDA(At, 0, 1); PG8_STAGE(PG8_SB(0, 0), b2, voffB); PG8_STAGE(PG8_SB(0, 1), b2 + hstep, voffB); PG8_STAGE(PG8_SA(0, 0), a2, voffA);
;             PG8_WAIT_V(8); PG8_WAIT_L(0); PG8_BAR; PG8_MMA(1, 0, At, B0); PG8_MMA(1, 1, At, B1); PG8_BAR; PG8_SCHED;
;             PG8_LDB(B0, 1, 0); PG8_LDB(B1, 1, 1); PG8_SCHED; PG8_LDA(At, 1, 0); PG8_STAGE(PG8_SA(0, 1), a2 + hstep, voffA);
;             PG8_WAIT_V(8); PG8_WAIT_L(0); PG8_BAR; PG8_MMA(0, 0, At, B0); PG8_MMA(0, 1, At, B1); PG8_BAR; PG8_SCHED;
	s_waitcnt lgkmcnt(0)
	v_mfma_f32_16x16x32_bf16 v[60:63], v[142:145], v[180:183], 0
	v_mfma_f32_16x16x32_bf16 v[56:59], v[150:153], v[180:183], 0
	v_mfma_f32_16x16x32_bf16 v[52:55], v[142:145], v[188:191], 0
	v_mfma_f32_16x16x32_bf16 v[48:51], v[150:153], v[188:191], 0
	v_mfma_f32_16x16x32_bf16 v[36:39], v[142:145], v[196:199], 0
	v_mfma_f32_16x16x32_bf16 v[32:35], v[150:153], v[196:199], 0
	v_mfma_f32_16x16x32_bf16 v[20:23], v[142:145], v[226:229], 0
	v_mfma_f32_16x16x32_bf16 v[16:19], v[150:153], v[226:229], 0
	v_mfma_f32_16x16x32_bf16 v[60:63], v[146:149], v[184:187], v[60:63]
	v_mfma_f32_16x16x32_bf16 v[56:59], v[154:157], v[184:187], v[56:59]
	v_mfma_f32_16x16x32_bf16 v[52:55], v[146:149], v[192:195], v[52:55]
	v_mfma_f32_16x16x32_bf16 v[48:51], v[154:157], v[192:195], v[48:51]
	v_mfma_f32_16x16x32_bf16 v[36:39], v[146:149], v[222:225], v[36:39]
	v_mfma_f32_16x16x32_bf16 v[32:35], v[154:157], v[222:225], v[32:35]
	v_mfma_f32_16x16x32_bf16 v[20:23], v[146:149], v[230:233], v[20:23]
	v_mfma_f32_16x16x32_bf16 v[16:19], v[154:157], v[230:233], v[16:19]
	v_mfma_f32_16x16x32_bf16 v[44:47], v[164:167], v[180:183], 0
	v_mfma_f32_16x16x32_bf16 v[40:43], v[172:175], v[180:183], 0
	v_mfma_f32_16x16x32_bf16 v[28:31], v[164:167], v[188:191], 0
	v_mfma_f32_16x16x32_bf16 v[24:27], v[172:175], v[188:191], 0
	v_mfma_f32_16x16x32_bf16 v[12:15], v[164:167], v[196:199], 0
	v_mfma_f32_16x16x32_bf16 v[8:11], v[172:175], v[196:199], 0
	v_mfma_f32_16x16x32_bf16 v[4:7], v[164:167], v[226:229], 0
	v_mfma_f32_16x16x32_bf16 v[0:3], v[172:175], v[226:229], 0
	v_mfma_f32_16x16x32_bf16 v[44:47], v[168:171], v[184:187], v[44:47]
	v_mfma_f32_16x16x32_bf16 v[40:43], v[176:179], v[184:187], v[40:43]
	v_mfma_f32_16x16x32_bf16 v[28:31], v[168:171], v[192:195], v[28:31]
	v_mfma_f32_16x16x32_bf16 v[24:27], v[176:179], v[192:195], v[24:27]
	v_mfma_f32_16x16x32_bf16 v[12:15], v[168:171], v[222:225], v[12:15]
	v_mfma_f32_16x16x32_bf16 v[8:11], v[176:179], v[222:225], v[8:11]
	v_mfma_f32_16x16x32_bf16 v[4:7], v[168:171], v[230:233], v[4:7]
	v_mfma_f32_16x16x32_bf16 v[0:3], v[176:179], v[230:233], v[0:3]
	s_barrier
	s_add_i32 s88, 0, 0x18000
	s_add_i32 s89, 0, 0x1c000
	ds_read_b128 v[142:145], v200 offset:32768
	ds_read_b128 v[146:149], v200 offset:33792
	ds_read_b128 v[150:153], v200 offset:34816
	ds_read_b128 v[154:157], v200 offset:35840
	ds_read_b128 v[164:167], v200 offset:49152
	ds_read_b128 v[168:171], v200 offset:50176
	ds_read_b128 v[172:175], v200 offset:51200
	ds_read_b128 v[176:179], v200 offset:52224
	s_add_u32 s52, s52, 0x80000
	s_addc_u32 s53, s53, 0
	s_mov_b32 m0, s56
	ds_read_b128 v[180:183], v141 offset:32768
	ds_read_b128 v[184:187], v141 offset:33792
	ds_read_b128 v[188:191], v141 offset:34816
	ds_read_b128 v[192:195], v141 offset:35840
	ds_read_b128 v[196:199], v141 offset:36864
	ds_read_b128 v[222:225], v141 offset:37888
	ds_read_b128 v[226:229], v141 offset:38912
	ds_read_b128 v[230:233], v141 offset:39936
	global_load_lds_dwordx4 v132, s[52:53]
	s_mov_b32 m0, s57
	s_nop 0
	global_load_lds_dwordx4 v130, s[52:53]
	s_waitcnt vmcnt(8)
	s_waitcnt lgkmcnt(0)
	s_barrier
	s_waitcnt lgkmcnt(0)
	v_mfma_f32_16x16x32_bf16 v[124:127], v[142:145], v[180:183], v[124:127]
	v_mfma_f32_16x16x32_bf16 v[120:123], v[150:153], v[180:183], v[120:123]
	v_mfma_f32_16x16x32_bf16 v[116:119], v[142:145], v[188:191], v[116:119]
	v_mfma_f32_16x16x32_bf16 v[112:115], v[150:153], v[188:191], v[112:115]
	v_mfma_f32_16x16x32_bf16 v[100:103], v[142:145], v[196:199], v[100:103]
	v_mfma_f32_16x16x32_bf16 v[96:99], v[150:153], v[196:199], v[96:99]
	v_mfma_f32_16x16x32_bf16 v[84:87], v[142:145], v[226:229], v[84:87]
	v_mfma_f32_16x16x32_bf16 v[80:83], v[150:153], v[226:229], v[80:83]
	v_mfma_f32_16x16x32_bf16 v[124:127], v[146:149], v[184:187], v[124:127]
	v_mfma_f32_16x16x32_bf16 v[120:123], v[154:157], v[184:187], v[120:123]
	v_mfma_f32_16x16x32_bf16 v[116:119], v[146:149], v[192:195], v[116:119]
	v_mfma_f32_16x16x32_bf16 v[112:115], v[154:157], v[192:195], v[112:115]
	v_mfma_f32_16x16x32_bf16 v[100:103], v[146:149], v[222:225], v[100:103]
	v_mfma_f32_16x16x32_bf16 v[96:99], v[154:157], v[222:225], v[96:99]
	v_mfma_f32_16x16x32_bf16 v[84:87], v[146:149], v[230:233], v[84:87]
	v_mfma_f32_16x16x32_bf16 v[80:83], v[154:157], v[230:233], v[80:83]
	v_mfma_f32_16x16x32_bf16 v[108:111], v[164:167], v[180:183], v[108:111]
	v_mfma_f32_16x16x32_bf16 v[104:107], v[172:175], v[180:183], v[104:107]
	v_mfma_f32_16x16x32_bf16 v[92:95], v[164:167], v[188:191], v[92:95]
	v_mfma_f32_16x16x32_bf16 v[88:91], v[172:175], v[188:191], v[88:91]
	v_mfma_f32_16x16x32_bf16 v[76:79], v[164:167], v[196:199], v[76:79]
	v_mfma_f32_16x16x32_bf16 v[72:75], v[172:175], v[196:199], v[72:75]
	v_mfma_f32_16x16x32_bf16 v[68:71], v[164:167], v[226:229], v[68:71]
	v_mfma_f32_16x16x32_bf16 v[64:67], v[172:175], v[226:229], v[64:67]
	v_mfma_f32_16x16x32_bf16 v[108:111], v[168:171], v[184:187], v[108:111]
	v_mfma_f32_16x16x32_bf16 v[104:107], v[176:179], v[184:187], v[104:107]
	v_mfma_f32_16x16x32_bf16 v[92:95], v[168:171], v[192:195], v[92:95]
	v_mfma_f32_16x16x32_bf16 v[88:91], v[176:179], v[192:195], v[88:91]
	v_mfma_f32_16x16x32_bf16 v[76:79], v[168:171], v[222:225], v[76:79]
	v_mfma_f32_16x16x32_bf16 v[72:75], v[176:179], v[222:225], v[72:75]
	v_mfma_f32_16x16x32_bf16 v[68:71], v[168:171], v[230:233], v[68:71]
	v_mfma_f32_16x16x32_bf16 v[64:67], v[176:179], v[230:233], v[64:67]
	s_barrier
; #define PG8_STAGE(bufoff, gbase, voff) do { _Pragma("unroll") for (int _i = 0; _i < 2; ++_i) \
;         __builtin_amdgcn_global_load_lds((const unsigned*)((const char*)(gbase) + (voff)[_i]), (PG8_LAS unsigned*)(lds + (bufoff) + ldsw + _i * 8192), 16, 0, 0); } while (0)
; #define PG8_LDA(dst, b, h) do { _Pragma("unroll") for (int m = 0; m < 4; ++m) _Pragma("unroll") for (int k = 0; k < 2; ++k) dst[m][k] = *(const PG8_LAS bf16x8*)(lds + PG8_SA(b, h) + aoff + m * 2048 + k * 1024); } while (0)
; #define PG8_MMA(ai, bj, At, Bt) do { __builtin_amdgcn_s_setprio(1); _Pragma("unroll") for (int m = 0; m < 4; ++m) _Pragma("unroll") for (int n = 0; n < 2; ++n) _Pragma("unroll") for (int k = 0; k < 2; ++k) \
;         acc[ai][bj][m][n] = __builtin_amdgcn_mfma_f32_16x16x32_bf16(Bt[n][k], At[m][k], acc[ai][bj][m][n], 0, 0, 0); __builtin_amdgcn_s_setprio(0); } while (0)
; #define PG8_WAIT_V(n) asm volatile("s_waitcnt vmcnt(" #n ")" ::: "memory")
; #define PG8_WAIT_L(n) asm volatile("s_waitcnt lgkmcnt(" #n ")" ::: "memory")
; #define PG8_BAR __builtin_amdgcn_s_barrier()
; #define PG8_SCHED __builtin_amdgcn_sched_barrier(0)
; template <class Epi, class Sched, bool ALIGN_EPI = false, bool SP2 = false>
; __device__ __forceinline__ void gemm_phase(PG8_LAS unsigned char* lds, const Gemm g, const Sched& S, const Epi& E) {
;     ...
;         for (int t = 0; t < nt; t += 2) {
;             const bool last = (t == nt - 2);
;             const char* a1 = cA + (size_t)(t + 1) * kstep;
;             const char* a2 = last ? nA : cA + (size_t)(t + 2) * kstep; const char* b2 = last ? nB : cB + (size_t)(t + 2) * kstep;
;     ...
;             PG8_WAIT_V(8); PG8_WAIT_L(0); PG8_BAR; PG8_MMA(0, 0, At, B0); PG8_MMA(0, 1, At, B1); PG8_BAR; PG8_SCHED;
;             PG8_LDA(At, 1, 1); PG8_STAGE(PG8_SB(1, 0), b3, voffB); PG8_STAGE(PG8_SB(1, 1), b3 + hstep, voffB); PG8_STAGE(PG8_SA(1, 0), a3, voffA);
;             PG8_WAIT_V(8); PG8_WAIT_L(0); PG8_BAR; PG8_MMA(1, 0, At, B0); PG8_MMA(1, 1, At, B1); PG8_BAR; PG8_SCHED;
	s_add_i32 s52, s88, s28
	s_mov_b32 m0, s52
	ds_read_b128 v[180:183], v141 offset:49152
	ds_read_b128 v[184:187], v141 offset:50176
	ds_read_b128 v[188:191], v141 offset:51200
	ds_read_b128 v[192:195], v141 offset:52224
	ds_read_b128 v[196:199], v141 offset:53248
	ds_read_b128 v[222:225], v141 offset:54272
	ds_read_b128 v[226:229], v141 offset:55296
	ds_read_b128 v[230:233], v141 offset:56320
	s_add_u32 s4, s4, 0x80
	s_addc_u32 s5, s5, 0
	global_load_lds_dwordx4 v160, s[4:5]
	s_add_i32 m0, s52, 0x2000
	s_add_i32 s52, s89, s28
	global_load_lds_dwordx4 v128, s[4:5]
	s_add_u32 s4, s4, 0x80000
	s_addc_u32 s5, s5, 0
	s_mov_b32 m0, s52
	s_nop 0
	global_load_lds_dwordx4 v160, s[4:5]
	s_add_i32 m0, s52, 0x2000
	s_nop 0
	global_load_lds_dwordx4 v128, s[4:5]
	s_mov_b32 m0, s24
	s_nop 0
	global_load_lds_dwordx4 v132, s[98:99]
	s_mov_b32 m0, s59
	s_nop 0
	global_load_lds_dwordx4 v130, s[98:99]
	s_waitcnt vmcnt(8)
	s_waitcnt lgkmcnt(0)
	s_barrier
	s_waitcnt lgkmcnt(0)
	v_mfma_f32_16x16x32_bf16 v[60:63], v[142:145], v[180:183], v[60:63]
	v_mfma_f32_16x16x32_bf16 v[56:59], v[150:153], v[180:183], v[56:59]
	v_mfma_f32_16x16x32_bf16 v[52:55], v[142:145], v[188:191], v[52:55]
	v_mfma_f32_16x16x32_bf16 v[48:51], v[150:153], v[188:191], v[48:51]
	v_mfma_f32_16x16x32_bf16 v[36:39], v[142:145], v[196:199], v[36:39]
	v_mfma_f32_16x16x32_bf16 v[32:35], v[150:153], v[196:199], v[32:35]
	v_mfma_f32_16x16x32_bf16 v[20:23], v[142:145], v[226:229], v[20:23]
	v_mfma_f32_16x16x32_bf16 v[16:19], v[150:153], v[226:229], v[16:19]
	v_mfma_f32_16x16x32_bf16 v[60:63], v[146:149], v[184:187], v[60:63]
	v_mfma_f32_16x16x32_bf16 v[56:59], v[154:157], v[184:187], v[56:59]
	v_mfma_f32_16x16x32_bf16 v[52:55], v[146:149], v[192:195], v[52:55]
	v_mfma_f32_16x16x32_bf16 v[48:51], v[154:157], v[192:195], v[48:51]
	v_mfma_f32_16x16x32_bf16 v[36:39], v[146:149], v[222:225], v[36:39]
	v_mfma_f32_16x16x32_bf16 v[32:35], v[154:157], v[222:225], v[32:35]
	v_mfma_f32_16x16x32_bf16 v[20:23], v[146:149], v[230:233], v[20:23]
	v_mfma_f32_16x16x32_bf16 v[16:19], v[154:157], v[230:233], v[16:19]
	v_mfma_f32_16x16x32_bf16 v[44:47], v[164:167], v[180:183], v[44:47]
	v_mfma_f32_16x16x32_bf16 v[40:43], v[172:175], v[180:183], v[40:43]
	v_mfma_f32_16x16x32_bf16 v[28:31], v[164:167], v[188:191], v[28:31]
	v_mfma_f32_16x16x32_bf16 v[24:27], v[172:175], v[188:191], v[24:27]
	v_mfma_f32_16x16x32_bf16 v[12:15], v[164:167], v[196:199], v[12:15]
	v_mfma_f32_16x16x32_bf16 v[8:11], v[172:175], v[196:199], v[8:11]
	v_mfma_f32_16x16x32_bf16 v[4:7], v[164:167], v[226:229], v[4:7]
	v_mfma_f32_16x16x32_bf16 v[0:3], v[172:175], v[226:229], v[0:3]
	v_mfma_f32_16x16x32_bf16 v[44:47], v[168:171], v[184:187], v[44:47]
	v_mfma_f32_16x16x32_bf16 v[40:43], v[176:179], v[184:187], v[40:43]
	v_mfma_f32_16x16x32_bf16 v[28:31], v[168:171], v[192:195], v[28:31]
	v_mfma_f32_16x16x32_bf16 v[24:27], v[176:179], v[192:195], v[24:27]
	v_mfma_f32_16x16x32_bf16 v[12:15], v[168:171], v[222:225], v[12:15]
	v_mfma_f32_16x16x32_bf16 v[8:11], v[176:179], v[222:225], v[8:11]
	v_mfma_f32_16x16x32_bf16 v[4:7], v[168:171], v[230:233], v[4:7]
	v_mfma_f32_16x16x32_bf16 v[0:3], v[176:179], v[230:233], v[0:3]
	s_barrier
	s_add_i32 s87, s87, 2
	s_add_u32 s80, s80, 0x100
	s_addc_u32 s81, s81, 0
	s_add_u32 s85, s85, 0x100
	s_addc_u32 s86, s86, 0

;     __host__ __device__ bool next(int i, Unit& u) const { if (!base.next(i >> 1, u)) return false; if (i & 1) { u.pm += 64; u.pn += 8; } return true; }
; #define PG8_STAGE(bufoff, gbase, voff) do { _Pragma("unroll") for (int _i = 0; _i < 2; ++_i) \
;         __builtin_amdgcn_global_load_lds((const unsigned*)((const char*)(gbase) + (voff)[_i]), (PG8_LAS unsigned*)(lds + (bufoff) + ldsw + _i * 8192), 16, 0, 0); } while (0)
; #define PG8_LDA(dst, b, h) do { _Pragma("unroll") for (int m = 0; m < 4; ++m) _Pragma("unroll") for (int k = 0; k < 2; ++k) dst[m][k] = *(const PG8_LAS bf16x8*)(lds + PG8_SA(b, h) + aoff + m * 2048 + k * 1024); } while (0)
; #define PG8_WAIT_V(n) asm volatile("s_waitcnt vmcnt(" #n ")" ::: "memory")
; #define PG8_WAIT_L(n) asm volatile("s_waitcnt lgkmcnt(" #n ")" ::: "memory")
; #define PG8_BAR __builtin_amdgcn_s_barrier()
; template <class Epi, class Sched, bool ALIGN_EPI = false, bool SP2 = false>
; __device__ __forceinline__ void gemm_phase(PG8_LAS unsigned char* lds, const Gemm g, const Sched& S, const Epi& E) {
;     ...
;         const bool has_next = S.next(ui + 1, nxt);
;         const char* nA = has_next ? (const char*)g.A + (size_t)nxt.pm * tstep : cA; const char* nB = has_next ? (const char*)g.Bt + (size_t)nxt.pn * tstep : cB;
;         for (int t = 0; t < nt; t += 2) {
;             const bool last = (t == nt - 2);
;             const char* a1 = cA + (size_t)(t + 1) * kstep;
;             const char* a2 = last ? nA : cA + (size_t)(t + 2) * kstep; const char* b2 = last ? nB : cB + (size_t)(t + 2) * kstep;
;             const char* a3 = a2 + kstep; const char* b3 = b2 + kstep;
;             if (last && has_next) S.a_ready(nxt);
;             if constexpr (SP2) {
;             PG8_LDB(B0, 0, 0); PG8_LDB(B1, 0, 1); PG8_SCHED; PG8_LDA(At, 0, 0); PG8_STAGE(PG8_SA(1, 1), a1 + hstep, voffA);
;             PG8_WAIT_V(8); PG8_WAIT_L(0); PG8_BAR; PG8_MMA(0, 0, At, B0); PG8_MMA(0, 1, At, B1); PG8_BAR; PG8_SCHED;
;             PG8_LDA(At, 0, 1); PG8_STAGE(PG8_SB(0, 0), b2, voffB); PG8_STAGE(PG8_SB(0, 1), b2 + hstep, voffB); PG8_STAGE(PG8_SA(0, 0), a2, voffA);
;     ...
;         for (int a = 0; a < 2; ++a)
; #pragma unroll
;             for (int b = 0; b < 2; ++b)
; #pragma unroll
;                 for (int m = 0; m < 4; ++m)
; #pragma unroll
;                     for (int n = 0; n < 2; ++n) acc[a][b][m][n] = (f32x4){0.f, 0.f, 0.f, 0.f};
.LBB0_848:
	s_ashr_i32 s11, s10, 31
	s_lshl_b64 s[42:43], s[10:11], 20
	s_add_u32 s42, s66, s42
	s_addc_u32 s43, s67, s43
	s_and_b64 s[44:45], s[14:15], exec
	s_cselect_b32 s11, s43, s53
	s_cselect_b32 s63, s42, s52
	s_ashr_i32 s13, s12, 31
	s_lshl_b64 s[44:45], s[12:13], 20
	s_add_u32 s44, s0, s44
	s_addc_u32 s45, s1, s45
	s_and_b64 s[70:71], s[14:15], exec
	s_cselect_b32 s13, s45, s5
	s_cselect_b32 s72, s44, s4
	s_add_u32 s70, s52, 0x80080
	s_addc_u32 s71, s53, 0
	s_add_u32 s73, s4, 0x100
	s_addc_u32 s74, s5, 0
	s_mov_b32 s75, -2
	v_add_u32_e32 v200, 0x10000, v141
	s_add_i32 s76, 0, 0x10000
	s_add_i32 s78, 0, 0x14000
	ds_read_b128 v[144:147], v200
	ds_read_b128 v[148:151], v200 offset:1024
	ds_read_b128 v[152:155], v200 offset:2048
	ds_read_b128 v[156:159], v200 offset:3072
	ds_read_b128 v[164:167], v200 offset:16384
	ds_read_b128 v[168:171], v200 offset:17408
	ds_read_b128 v[172:175], v200 offset:18432
	ds_read_b128 v[176:179], v200 offset:19456
	s_add_i32 m0, s51, 0xc000
	ds_read_b128 v[180:183], v143
	ds_read_b128 v[184:187], v143 offset:1024
	ds_read_b128 v[188:191], v143 offset:2048
	ds_read_b128 v[192:195], v143 offset:3072
	ds_read_b128 v[196:199], v143 offset:4096
	ds_read_b128 v[222:225], v143 offset:5120
	ds_read_b128 v[226:229], v143 offset:6144
	ds_read_b128 v[230:233], v143 offset:7168
	global_load_lds_dwordx4 v134, s[70:71]
	s_add_i32 m0, s51, 0xe000
	s_nop 0
	global_load_lds_dwordx4 v136, s[70:71]
	s_add_u32 s4, s70, 0xfff80080
	s_addc_u32 s5, s71, -1
	s_cmp_eq_u32 s75, 28
	s_cselect_b32 s53, s11, s5
	s_cselect_b32 s52, s63, s4
	s_cselect_b32 s5, s13, s74
	s_cselect_b32 s4, s72, s73
	s_waitcnt vmcnt(8)
	s_waitcnt lgkmcnt(0)
	s_barrier
	s_waitcnt lgkmcnt(0)
	v_mfma_f32_16x16x32_bf16 v[124:127], v[144:147], v[180:183], 0
	v_mfma_f32_16x16x32_bf16 v[116:119], v[152:155], v[180:183], 0
	v_mfma_f32_16x16x32_bf16 v[108:111], v[144:147], v[188:191], 0
	v_mfma_f32_16x16x32_bf16 v[100:103], v[152:155], v[188:191], 0
	v_mfma_f32_16x16x32_bf16 v[92:95], v[144:147], v[196:199], 0
	v_mfma_f32_16x16x32_bf16 v[84:87], v[152:155], v[196:199], 0
	v_mfma_f32_16x16x32_bf16 v[76:79], v[144:147], v[226:229], 0
	v_mfma_f32_16x16x32_bf16 v[68:71], v[152:155], v[226:229], 0
	v_mfma_f32_16x16x32_bf16 v[124:127], v[148:151], v[184:187], v[124:127]
	v_mfma_f32_16x16x32_bf16 v[116:119], v[156:159], v[184:187], v[116:119]
	v_mfma_f32_16x16x32_bf16 v[108:111], v[148:151], v[192:195], v[108:111]
	v_mfma_f32_16x16x32_bf16 v[100:103], v[156:159], v[192:195], v[100:103]
	v_mfma_f32_16x16x32_bf16 v[92:95], v[148:151], v[222:225], v[92:95]
	v_mfma_f32_16x16x32_bf16 v[84:87], v[156:159], v[222:225], v[84:87]
	v_mfma_f32_16x16x32_bf16 v[76:79], v[148:151], v[230:233], v[76:79]
	v_mfma_f32_16x16x32_bf16 v[68:71], v[156:159], v[230:233], v[68:71]
	v_mfma_f32_16x16x32_bf16 v[120:123], v[164:167], v[180:183], 0
	v_mfma_f32_16x16x32_bf16 v[112:115], v[172:175], v[180:183], 0
	v_mfma_f32_16x16x32_bf16 v[104:107], v[164:167], v[188:191], 0
	v_mfma_f32_16x16x32_bf16 v[96:99], v[172:175], v[188:191], 0
	v_mfma_f32_16x16x32_bf16 v[88:91], v[164:167], v[196:199], 0
	v_mfma_f32_16x16x32_bf16 v[80:83], v[172:175], v[196:199], 0
	v_mfma_f32_16x16x32_bf16 v[72:75], v[164:167], v[226:229], 0
	v_mfma_f32_16x16x32_bf16 v[64:67], v[172:175], v[226:229], 0
	v_mfma_f32_16x16x32_bf16 v[120:123], v[168:171], v[184:187], v[120:123]
	v_mfma_f32_16x16x32_bf16 v[112:115], v[176:179], v[184:187], v[112:115]
	v_mfma_f32_16x16x32_bf16 v[104:107], v[168:171], v[192:195], v[104:107]
	v_mfma_f32_16x16x32_bf16 v[96:99], v[176:179], v[192:195], v[96:99]
	v_mfma_f32_16x16x32_bf16 v[88:91], v[168:171], v[222:225], v[88:91]
	v_mfma_f32_16x16x32_bf16 v[80:83], v[176:179], v[222:225], v[80:83]
	v_mfma_f32_16x16x32_bf16 v[72:75], v[168:171], v[230:233], v[72:75]
	v_mfma_f32_16x16x32_bf16 v[64:67], v[176:179], v[230:233], v[64:67]
	s_barrier
	s_add_i32 s76, s76, s24
	s_mov_b32 m0, s76
	ds_read_b128 v[180:183], v143 offset:16384
	ds_read_b128 v[184:187], v143 offset:17408
	ds_read_b128 v[188:191], v143 offset:18432
	ds_read_b128 v[192:195], v143 offset:19456
	ds_read_b128 v[196:199], v143 offset:20480
	ds_read_b128 v[222:225], v143 offset:21504
	ds_read_b128 v[226:229], v143 offset:22528
	ds_read_b128 v[230:233], v143 offset:23552
	global_load_lds_dwordx4 v160, s[4:5]
	s_add_i32 m0, s76, 0x2000
	s_add_u32 s76, s4, 0x80000
	s_addc_u32 s77, s5, 0
	s_add_i32 s78, s78, s24
	global_load_lds_dwordx4 v128, s[4:5]
	s_mov_b32 m0, s78
	s_nop 0
	global_load_lds_dwordx4 v160, s[76:77]
	s_add_i32 m0, s78, 0x2000
	s_nop 0
	global_load_lds_dwordx4 v128, s[76:77]
	s_mov_b32 m0, s51
	s_nop 0
	global_load_lds_dwordx4 v132, s[52:53]
	s_mov_b32 m0, s55
	s_nop 0
	global_load_lds_dwordx4 v130, s[52:53]
	s_add_u32 s98, s52, 0x80
	s_addc_u32 s99, s53, 0
	s_waitcnt vmcnt(8)
	s_waitcnt lgkmcnt(0)
	s_barrier
; #define PG8_STAGE(bufoff, gbase, voff) do { _Pragma("unroll") for (int _i = 0; _i < 2; ++_i) \
;         __builtin_amdgcn_global_load_lds((const unsigned*)((const char*)(gbase) + (voff)[_i]), (PG8_LAS unsigned*)(lds + (bufoff) + ldsw + _i * 8192), 16, 0, 0); } while (0)
; #define PG8_LDA(dst, b, h) do { _Pragma("unroll") for (int m = 0; m < 4; ++m) _Pragma("unroll") for (int k = 0; k < 2; ++k) dst[m][k] = *(const PG8_LAS bf16x8*)(lds + PG8_SA(b, h) + aoff + m * 2048 + k * 1024); } while (0)
; #define PG8_LDB(dst, b, h) do { _Pragma("unroll") for (int n = 0; n < 2; ++n) _Pragma("unroll") for (int k = 0; k < 2; ++k) dst[n][k] = *(const PG8_LAS bf16x8*)(lds + PG8_SB(b, h) + boff + n * 2048 + k * 1024); } while (0)
; #define PG8_MMA(ai, bj, At, Bt) do { __builtin_amdgcn_s_setprio(1); _Pragma("unroll") for (int m = 0; m < 4; ++m) _Pragma("unroll") for (int n = 0; n < 2; ++n) _Pragma("unroll") for (int k = 0; k < 2; ++k) \
;         acc[ai][bj][m][n] = __builtin_amdgcn_mfma_f32_16x16x32_bf16(Bt[n][k], At[m][k], acc[ai][bj][m][n], 0, 0, 0); __builtin_amdgcn_s_setprio(0); } while (0)
; #define PG8_WAIT_V(n) asm volatile("s_waitcnt vmcnt(" #n ")" ::: "memory")
; #define PG8_WAIT_L(n) asm volatile("s_waitcnt lgkmcnt(" #n ")" ::: "memory")
; #define PG8_BAR __builtin_amdgcn_s_barrier()
; #define PG8_SCHED __builtin_amdgcn_sched_barrier(0)
; template <class Epi, class Sched, bool ALIGN_EPI = false, bool SP2 = false>
; __device__ __forceinline__ void gemm_phase(PG8_LAS unsigned char* lds, const Gemm g, const Sched& S, const Epi& E) {
;     ...
;             PG8_WAIT_V(8); PG8_WAIT_L(0); PG8_BAR; PG8_MMA(0, 0, At, B0); PG8_MMA(0, 1, At, B1); PG8_BAR; PG8_SCHED;
;             PG8_LDA(At, 0, 1); PG8_STAGE(PG8_SB(0, 0), b2, voffB); PG8_STAGE(PG8_SB(0, 1), b2 + hstep, voffB); PG8_STAGE(PG8_SA(0, 0), a2, voffA);
;             PG8_WAIT_V(8); PG8_WAIT_L(0); PG8_BAR; PG8_MMA(1, 0, At, B0); PG8_MMA(1, 1, At, B1); PG8_BAR; PG8_SCHED;
;             PG8_LDB(B0, 1, 0); PG8_LDB(B1, 1, 1); PG8_SCHED; PG8_LDA(At, 1, 0); PG8_STAGE(PG8_SA(0, 1), a2 + hstep, voffA);
;             PG8_WAIT_V(8); PG8_WAIT_L(0); PG8_BAR; PG8_MMA(0, 0, At, B0); PG8_MMA(0, 1, At, B1); PG8_BAR; PG8_SCHED;
	s_waitcnt lgkmcnt(0)
	v_mfma_f32_16x16x32_bf16 v[60:63], v[144:147], v[180:183], 0
	v_mfma_f32_16x16x32_bf16 v[52:55], v[152:155], v[180:183], 0
	v_mfma_f32_16x16x32_bf16 v[44:47], v[144:147], v[188:191], 0
	v_mfma_f32_16x16x32_bf16 v[36:39], v[152:155], v[188:191], 0
	v_mfma_f32_16x16x32_bf16 v[28:31], v[144:147], v[196:199], 0
	v_mfma_f32_16x16x32_bf16 v[20:23], v[152:155], v[196:199], 0
	v_mfma_f32_16x16x32_bf16 v[12:15], v[144:147], v[226:229], 0
	v_mfma_f32_16x16x32_bf16 v[4:7], v[152:155], v[226:229], 0
	v_mfma_f32_16x16x32_bf16 v[60:63], v[148:151], v[184:187], v[60:63]
	v_mfma_f32_16x16x32_bf16 v[52:55], v[156:159], v[184:187], v[52:55]
	v_mfma_f32_16x16x32_bf16 v[44:47], v[148:151], v[192:195], v[44:47]
	v_mfma_f32_16x16x32_bf16 v[36:39], v[156:159], v[192:195], v[36:39]
	v_mfma_f32_16x16x32_bf16 v[28:31], v[148:151], v[222:225], v[28:31]
	v_mfma_f32_16x16x32_bf16 v[20:23], v[156:159], v[222:225], v[20:23]
	v_mfma_f32_16x16x32_bf16 v[12:15], v[148:151], v[230:233], v[12:15]
	v_mfma_f32_16x16x32_bf16 v[4:7], v[156:159], v[230:233], v[4:7]
	v_mfma_f32_16x16x32_bf16 v[56:59], v[164:167], v[180:183], 0
	v_mfma_f32_16x16x32_bf16 v[48:51], v[172:175], v[180:183], 0
	v_mfma_f32_16x16x32_bf16 v[40:43], v[164:167], v[188:191], 0
	v_mfma_f32_16x16x32_bf16 v[32:35], v[172:175], v[188:191], 0
	v_mfma_f32_16x16x32_bf16 v[24:27], v[164:167], v[196:199], 0
	v_mfma_f32_16x16x32_bf16 v[16:19], v[172:175], v[196:199], 0
	v_mfma_f32_16x16x32_bf16 v[8:11], v[164:167], v[226:229], 0
	v_mfma_f32_16x16x32_bf16 v[0:3], v[172:175], v[226:229], 0
	v_mfma_f32_16x16x32_bf16 v[56:59], v[168:171], v[184:187], v[56:59]
	v_mfma_f32_16x16x32_bf16 v[48:51], v[176:179], v[184:187], v[48:51]
	v_mfma_f32_16x16x32_bf16 v[40:43], v[168:171], v[192:195], v[40:43]
	v_mfma_f32_16x16x32_bf16 v[32:35], v[176:179], v[192:195], v[32:35]
	v_mfma_f32_16x16x32_bf16 v[24:27], v[168:171], v[222:225], v[24:27]
	v_mfma_f32_16x16x32_bf16 v[16:19], v[176:179], v[222:225], v[16:19]
	v_mfma_f32_16x16x32_bf16 v[8:11], v[168:171], v[230:233], v[8:11]
	v_mfma_f32_16x16x32_bf16 v[0:3], v[176:179], v[230:233], v[0:3]
	s_barrier
	s_add_i32 s76, 0, 0x18000
	s_add_i32 s77, 0, 0x1c000
	ds_read_b128 v[144:147], v200 offset:32768
	ds_read_b128 v[148:151], v200 offset:33792
	ds_read_b128 v[152:155], v200 offset:34816
	ds_read_b128 v[156:159], v200 offset:35840
	ds_read_b128 v[164:167], v200 offset:49152
	ds_read_b128 v[168:171], v200 offset:50176
	ds_read_b128 v[172:175], v200 offset:51200
	ds_read_b128 v[176:179], v200 offset:52224
	s_add_u32 s52, s52, 0x80000
	s_addc_u32 s53, s53, 0
	s_mov_b32 m0, s56
	ds_read_b128 v[180:183], v143 offset:32768
	ds_read_b128 v[184:187], v143 offset:33792
	ds_read_b128 v[188:191], v143 offset:34816
	ds_read_b128 v[192:195], v143 offset:35840
	ds_read_b128 v[196:199], v143 offset:36864
	ds_read_b128 v[222:225], v143 offset:37888
	ds_read_b128 v[226:229], v143 offset:38912
	ds_read_b128 v[230:233], v143 offset:39936
	global_load_lds_dwordx4 v132, s[52:53]
	s_mov_b32 m0, s57
	s_nop 0
	global_load_lds_dwordx4 v130, s[52:53]
	s_waitcnt vmcnt(8)
	s_waitcnt lgkmcnt(0)
	s_barrier
	s_waitcnt lgkmcnt(0)
	v_mfma_f32_16x16x32_bf16 v[124:127], v[144:147], v[180:183], v[124:127]
	v_mfma_f32_16x16x32_bf16 v[116:119], v[152:155], v[180:183], v[116:119]
	v_mfma_f32_16x16x32_bf16 v[108:111], v[144:147], v[188:191], v[108:111]
	v_mfma_f32_16x16x32_bf16 v[100:103], v[152:155], v[188:191], v[100:103]
	v_mfma_f32_16x16x32_bf16 v[92:95], v[144:147], v[196:199], v[92:95]
	v_mfma_f32_16x16x32_bf16 v[84:87], v[152:155], v[196:199], v[84:87]
	v_mfma_f32_16x16x32_bf16 v[76:79], v[144:147], v[226:229], v[76:79]
	v_mfma_f32_16x16x32_bf16 v[68:71], v[152:155], v[226:229], v[68:71]
	v_mfma_f32_16x16x32_bf16 v[124:127], v[148:151], v[184:187], v[124:127]
	v_mfma_f32_16x16x32_bf16 v[116:119], v[156:159], v[184:187], v[116:119]
	v_mfma_f32_16x16x32_bf16 v[108:111], v[148:151], v[192:195], v[108:111]
	v_mfma_f32_16x16x32_bf16 v[100:103], v[156:159], v[192:195], v[100:103]
	v_mfma_f32_16x16x32_bf16 v[92:95], v[148:151], v[222:225], v[92:95]
	v_mfma_f32_16x16x32_bf16 v[84:87], v[156:159], v[222:225], v[84:87]
	v_mfma_f32_16x16x32_bf16 v[76:79], v[148:151], v[230:233], v[76:79]
	v_mfma_f32_16x16x32_bf16 v[68:71], v[156:159], v[230:233], v[68:71]
	v_mfma_f32_16x16x32_bf16 v[120:123], v[164:167], v[180:183], v[120:123]
	v_mfma_f32_16x16x32_bf16 v[112:115], v[172:175], v[180:183], v[112:115]
	v_mfma_f32_16x16x32_bf16 v[104:107], v[164:167], v[188:191], v[104:107]
	v_mfma_f32_16x16x32_bf16 v[96:99], v[172:175], v[188:191], v[96:99]
	v_mfma_f32_16x16x32_bf16 v[88:91], v[164:167], v[196:199], v[88:91]
	v_mfma_f32_16x16x32_bf16 v[80:83], v[172:175], v[196:199], v[80:83]
	v_mfma_f32_16x16x32_bf16 v[72:75], v[164:167], v[226:229], v[72:75]
	v_mfma_f32_16x16x32_bf16 v[64:67], v[172:175], v[226:229], v[64:67]
	v_mfma_f32_16x16x32_bf16 v[120:123], v[168:171], v[184:187], v[120:123]
	v_mfma_f32_16x16x32_bf16 v[112:115], v[176:179], v[184:187], v[112:115]
	v_mfma_f32_16x16x32_bf16 v[104:107], v[168:171], v[192:195], v[104:107]
	v_mfma_f32_16x16x32_bf16 v[96:99], v[176:179], v[192:195], v[96:99]
	v_mfma_f32_16x16x32_bf16 v[88:91], v[168:171], v[222:225], v[88:91]
	v_mfma_f32_16x16x32_bf16 v[80:83], v[176:179], v[222:225], v[80:83]
	v_mfma_f32_16x16x32_bf16 v[72:75], v[168:171], v[230:233], v[72:75]
	v_mfma_f32_16x16x32_bf16 v[64:67], v[176:179], v[230:233], v[64:67]
	s_barrier
; #define PG8_STAGE(bufoff, gbase, voff) do { _Pragma("unroll") for (int _i = 0; _i < 2; ++_i) \
;         __builtin_amdgcn_global_load_lds((const unsigned*)((const char*)(gbase) + (voff)[_i]), (PG8_LAS unsigned*)(lds + (bufoff) + ldsw + _i * 8192), 16, 0, 0); } while (0)
; #define PG8_LDA(dst, b, h) do { _Pragma("unroll") for (int m = 0; m < 4; ++m) _Pragma("unroll") for (int k = 0; k < 2; ++k) dst[m][k] = *(const PG8_LAS bf16x8*)(lds + PG8_SA(b, h) + aoff + m * 2048 + k * 1024); } while (0)
; #define PG8_MMA(ai, bj, At, Bt) do { __builtin_amdgcn_s_setprio(1); _Pragma("unroll") for (int m = 0; m < 4; ++m) _Pragma("unroll") for (int n = 0; n < 2; ++n) _Pragma("unroll") for (int k = 0; k < 2; ++k) \
;         acc[ai][bj][m][n] = __builtin_amdgcn_mfma_f32_16x16x32_bf16(Bt[n][k], At[m][k], acc[ai][bj][m][n], 0, 0, 0); __builtin_amdgcn_s_setprio(0); } while (0)
; #define PG8_WAIT_V(n) asm volatile("s_waitcnt vmcnt(" #n ")" ::: "memory")
; #define PG8_WAIT_L(n) asm volatile("s_waitcnt lgkmcnt(" #n ")" ::: "memory")
; #define PG8_BAR __builtin_amdgcn_s_barrier()
; #define PG8_SCHED __builtin_amdgcn_sched_barrier(0)
; template <class Epi, class Sched, bool ALIGN_EPI = false, bool SP2 = false>
; __device__ __forceinline__ void gemm_phase(PG8_LAS unsigned char* lds, const Gemm g, const Sched& S, const Epi& E) {
;     ...
;         for (int t = 0; t < nt; t += 2) {
;             const bool last = (t == nt - 2);
;             const char* a1 = cA + (size_t)(t + 1) * kstep;
;             const char* a2 = last ? nA : cA + (size_t)(t + 2) * kstep; const char* b2 = last ? nB : cB + (size_t)(t + 2) * kstep;
;     ...
;             PG8_WAIT_V(8); PG8_WAIT_L(0); PG8_BAR; PG8_MMA(0, 0, At, B0); PG8_MMA(0, 1, At, B1); PG8_BAR; PG8_SCHED;
;             PG8_LDA(At, 1, 1); PG8_STAGE(PG8_SB(1, 0), b3, voffB); PG8_STAGE(PG8_SB(1, 1), b3 + hstep, voffB); PG8_STAGE(PG8_SA(1, 0), a3, voffA);
;             PG8_WAIT_V(8); PG8_WAIT_L(0); PG8_BAR; PG8_MMA(1, 0, At, B0); PG8_MMA(1, 1, At, B1); PG8_BAR; PG8_SCHED;
	s_add_i32 s52, s76, s24
	s_mov_b32 m0, s52
	ds_read_b128 v[180:183], v143 offset:49152
	ds_read_b128 v[184:187], v143 offset:50176
	ds_read_b128 v[188:191], v143 offset:51200
	ds_read_b128 v[192:195], v143 offset:52224
	ds_read_b128 v[196:199], v143 offset:53248
	ds_read_b128 v[222:225], v143 offset:54272
	ds_read_b128 v[226:229], v143 offset:55296
	ds_read_b128 v[230:233], v143 offset:56320
	s_add_u32 s4, s4, 0x80
	s_addc_u32 s5, s5, 0
	global_load_lds_dwordx4 v160, s[4:5]
	s_add_i32 m0, s52, 0x2000
	s_add_i32 s52, s77, s24
	global_load_lds_dwordx4 v128, s[4:5]
	s_add_u32 s4, s4, 0x80000
	s_addc_u32 s5, s5, 0
	s_mov_b32 m0, s52
	s_nop 0
	global_load_lds_dwordx4 v160, s[4:5]
	s_add_i32 m0, s52, 0x2000
	s_nop 0
	global_load_lds_dwordx4 v128, s[4:5]
	s_mov_b32 m0, s58
	s_nop 0
	global_load_lds_dwordx4 v132, s[98:99]
	s_mov_b32 m0, s59
	s_nop 0
	global_load_lds_dwordx4 v130, s[98:99]
	s_waitcnt vmcnt(8)
	s_waitcnt lgkmcnt(0)
	s_barrier
	s_waitcnt lgkmcnt(0)
	v_mfma_f32_16x16x32_bf16 v[60:63], v[144:147], v[180:183], v[60:63]
	v_mfma_f32_16x16x32_bf16 v[52:55], v[152:155], v[180:183], v[52:55]
	v_mfma_f32_16x16x32_bf16 v[44:47], v[144:147], v[188:191], v[44:47]
	v_mfma_f32_16x16x32_bf16 v[36:39], v[152:155], v[188:191], v[36:39]
	v_mfma_f32_16x16x32_bf16 v[28:31], v[144:147], v[196:199], v[28:31]
	v_mfma_f32_16x16x32_bf16 v[20:23], v[152:155], v[196:199], v[20:23]
	v_mfma_f32_16x16x32_bf16 v[12:15], v[144:147], v[226:229], v[12:15]
	v_mfma_f32_16x16x32_bf16 v[4:7], v[152:155], v[226:229], v[4:7]
	v_mfma_f32_16x16x32_bf16 v[60:63], v[148:151], v[184:187], v[60:63]
	v_mfma_f32_16x16x32_bf16 v[52:55], v[156:159], v[184:187], v[52:55]
	v_mfma_f32_16x16x32_bf16 v[44:47], v[148:151], v[192:195], v[44:47]
	v_mfma_f32_16x16x32_bf16 v[36:39], v[156:159], v[192:195], v[36:39]
	v_mfma_f32_16x16x32_bf16 v[28:31], v[148:151], v[222:225], v[28:31]
	v_mfma_f32_16x16x32_bf16 v[20:23], v[156:159], v[222:225], v[20:23]
	v_mfma_f32_16x16x32_bf16 v[12:15], v[148:151], v[230:233], v[12:15]
	v_mfma_f32_16x16x32_bf16 v[4:7], v[156:159], v[230:233], v[4:7]
	v_mfma_f32_16x16x32_bf16 v[56:59], v[164:167], v[180:183], v[56:59]
	v_mfma_f32_16x16x32_bf16 v[48:51], v[172:175], v[180:183], v[48:51]
	v_mfma_f32_16x16x32_bf16 v[40:43], v[164:167], v[188:191], v[40:43]
	v_mfma_f32_16x16x32_bf16 v[32:35], v[172:175], v[188:191], v[32:35]
	v_mfma_f32_16x16x32_bf16 v[24:27], v[164:167], v[196:199], v[24:27]
	v_mfma_f32_16x16x32_bf16 v[16:19], v[172:175], v[196:199], v[16:19]
	v_mfma_f32_16x16x32_bf16 v[8:11], v[164:167], v[226:229], v[8:11]
	v_mfma_f32_16x16x32_bf16 v[0:3], v[172:175], v[226:229], v[0:3]
	v_mfma_f32_16x16x32_bf16 v[56:59], v[168:171], v[184:187], v[56:59]
	v_mfma_f32_16x16x32_bf16 v[48:51], v[176:179], v[184:187], v[48:51]
	v_mfma_f32_16x16x32_bf16 v[40:43], v[168:171], v[192:195], v[40:43]
	v_mfma_f32_16x16x32_bf16 v[32:35], v[176:179], v[192:195], v[32:35]
	v_mfma_f32_16x16x32_bf16 v[24:27], v[168:171], v[222:225], v[24:27]
	v_mfma_f32_16x16x32_bf16 v[16:19], v[176:179], v[222:225], v[16:19]
	v_mfma_f32_16x16x32_bf16 v[8:11], v[168:171], v[230:233], v[8:11]
	v_mfma_f32_16x16x32_bf16 v[0:3], v[176:179], v[230:233], v[0:3]
	s_barrier
	s_add_i32 s75, s75, 2
	s_add_u32 s70, s70, 0x100
	s_addc_u32 s71, s71, 0
	s_add_u32 s73, s73, 0x100
	s_addc_u32 s74, s74, 0
